# P1 epilogue, memory-query unit: the four gain quads and the seven later sum-of-squares values loaded once at the top of the path, in-slice loads become moves, per-slice waits removed
# baseline (speedup 1.0000x reference)
.LBB0_165:
	global_load_dwordx4 v[212:215], v[154:155], off
	global_load_dwordx4 v[216:219], v[154:155], off offset:16
	global_load_dwordx4 v[220:223], v[154:155], off offset:128
	global_load_dwordx4 v[224:227], v[154:155], off offset:144
	global_load_dword v228, v[168:169], off offset:64
	global_load_dword v229, v[168:169], off offset:128
	global_load_dword v230, v[168:169], off offset:192
	global_load_dword v231, v[168:169], off offset:512
	global_load_dword v232, v[168:169], off offset:576
	global_load_dword v233, v[168:169], off offset:640
	global_load_dword v234, v[168:169], off offset:704
	v_and_b32_e32 v196, 64, v188
	v_pk_mul_f32 v[130:131], v[128:129], v[170:171] op_sel_hi:[1,0]
	v_pk_mul_f32 v[132:133], v[126:127], v[170:171] op_sel_hi:[1,0]
	v_pk_mul_f32 v[142:143], v[120:121], v[170:171] op_sel_hi:[1,0]
	v_pk_mul_f32 v[144:145], v[118:119], v[170:171] op_sel_hi:[1,0]
	v_pk_mul_f32 v[190:191], v[122:123], v[170:171] op_sel_hi:[1,0]
	v_add_u32_e32 v201, 64, v196
	v_pk_mul_f32 v[130:131], v[130:131], v[130:131]
	v_pk_mul_f32 v[196:197], v[132:133], v[132:133]
	v_pk_mul_f32 v[132:133], v[142:143], v[142:143]
	v_pk_mul_f32 v[142:143], v[144:145], v[144:145]
	v_pk_mul_f32 v[172:173], v[124:125], v[170:171] op_sel_hi:[1,0]
	v_mul_f32_e32 v144, v190, v190
	v_pk_mov_b32 v[202:203], v[196:197], v[130:131] op_sel:[1,0]
	v_mov_b32_e32 v197, v131
	v_pk_mov_b32 v[130:131], v[142:143], v[132:133] op_sel:[1,0]
	v_mov_b32_e32 v143, v133
	v_mul_f32_e32 v200, v172, v172
	v_pk_fma_f32 v[144:145], v[190:191], v[190:191], v[144:145] op_sel_hi:[1,1,0]
	v_pk_add_f32 v[190:191], v[202:203], v[196:197]
	v_pk_add_f32 v[130:131], v[130:131], v[142:143]
	v_pk_mul_f32 v[192:193], v[116:117], v[170:171] op_sel_hi:[1,0]
	v_pk_mul_f32 v[194:195], v[114:115], v[170:171] op_sel_hi:[1,0]
	v_pk_fma_f32 v[172:173], v[172:173], v[172:173], v[200:201] op_sel_hi:[1,1,0]
	v_pk_add_f32 v[142:143], v[190:191], v[190:191] op_sel_hi:[0,1]
	v_pk_add_f32 v[130:131], v[130:131], v[130:131] op_sel_hi:[0,1]
	v_xor_b32_e32 v189, 16, v188
	v_mul_f32_e32 v144, v194, v194
	v_mul_f32_e32 v172, v195, v195
	v_mul_f32_e32 v142, v192, v192
	v_mul_f32_e32 v130, v193, v193
	v_cmp_lt_i32_e32 vcc, v189, v201
	v_pk_add_f32 v[144:145], v[144:145], v[172:173]
	v_pk_add_f32 v[130:131], v[142:143], v[130:131]
	v_cndmask_b32_e32 v189, v188, v189, vcc
	v_pk_add_f32 v[130:131], v[144:145], v[130:131]
	v_lshlrev_b32_e32 v132, 2, v189
	v_add_f32_e32 v130, v130, v131
	ds_bpermute_b32 v131, v132, v130
	v_xor_b32_e32 v133, 32, v188
	v_cmp_lt_i32_e32 vcc, v133, v201
	s_mov_b32 s0, 0x10000
	s_waitcnt lgkmcnt(0)
	v_add_f32_e32 v130, v130, v131
	v_cndmask_b32_e32 v133, v188, v133, vcc
	v_lshlrev_b32_e32 v133, 2, v133
	ds_bpermute_b32 v131, v133, v130
	s_waitcnt lgkmcnt(0)
	v_add_f32_e32 v130, v130, v131
	v_fmamk_f32 v130, v130, 0x3c800000, v187
	v_rsq_f32_e32 v142, v130
	v_lshlrev_b64 v[130:131], 9, v[166:167]
	v_lshl_add_u64 v[130:131], v[156:157], 0, v[130:131]
	v_mul_f32_e32 v142, v170, v142
	v_mul_f32_e32 v142, 0x3e38aa3b, v142
	v_pk_mul_f32 v[144:145], v[126:127], v[142:143] op_sel_hi:[1,0]
	v_pk_mul_f32 v[172:173], v[128:129], v[142:143] op_sel_hi:[1,0]
	v_pk_mul_f32 v[190:191], v[118:119], v[142:143] op_sel_hi:[1,0]
	v_pk_mul_f32 v[192:193], v[120:121], v[142:143] op_sel_hi:[1,0]
	v_pk_mul_f32 v[194:195], v[114:115], v[142:143] op_sel_hi:[1,0]
	s_waitcnt vmcnt(0)
	v_mov_b32_e32 v134, v212
	v_mov_b32_e32 v135, v213
	v_mov_b32_e32 v136, v214
	v_mov_b32_e32 v137, v215
	v_mov_b32_e32 v138, v216
	v_mov_b32_e32 v139, v217
	v_mov_b32_e32 v140, v218
	v_mov_b32_e32 v141, v219
	v_pk_mul_f32 v[136:137], v[136:137], v[172:173]
	v_pk_mul_f32 v[134:135], v[134:135], v[144:145]
	v_pk_mul_f32 v[140:141], v[140:141], v[192:193]
	v_pk_mul_f32 v[138:139], v[138:139], v[190:191]
	v_cvt_pk_bf16_f32 v134, v134, v135
	v_cvt_pk_bf16_f32 v135, v136, v137
	v_cvt_pk_bf16_f32 v136, v138, v139
	v_cvt_pk_bf16_f32 v137, v140, v141
	global_store_dwordx4 v[130:131], v[134:137], off
	s_nop 1
	v_mov_b32_e32 v134, v220
	v_mov_b32_e32 v135, v221
	v_mov_b32_e32 v136, v222
	v_mov_b32_e32 v137, v223
	s_nop 0
	s_nop 1
	v_mov_b32_e32 v138, v224
	v_mov_b32_e32 v139, v225
	v_mov_b32_e32 v140, v226
	v_mov_b32_e32 v141, v227
	v_pk_mul_f32 v[190:191], v[122:123], v[142:143] op_sel_hi:[1,0]
	v_pk_mul_f32 v[192:193], v[124:125], v[142:143] op_sel_hi:[1,0]
	v_pk_mul_f32 v[142:143], v[116:117], v[142:143] op_sel_hi:[1,0]
	v_or_b32_e32 v144, 16, v166
	v_ashrrev_i32_e32 v145, 31, v144
	v_lshl_add_u64 v[172:173], v[144:145], 2, s[16:17]
	v_lshlrev_b64 v[144:145], 9, v[144:145]
	v_lshl_add_u64 v[144:145], v[156:157], 0, v[144:145]
	v_pk_mul_f32 v[136:137], v[136:137], v[192:193]
	v_pk_mul_f32 v[134:135], v[134:135], v[190:191]
	v_pk_mul_f32 v[140:141], v[140:141], v[142:143]
	v_pk_mul_f32 v[138:139], v[138:139], v[194:195]
	v_cvt_pk_bf16_f32 v134, v134, v135
	v_cvt_pk_bf16_f32 v135, v136, v137
	v_cvt_pk_bf16_f32 v136, v138, v139
	v_cvt_pk_bf16_f32 v137, v140, v141
	global_store_dwordx4 v[130:131], v[134:137], off offset:64
	s_nop 1
	v_mov_b32_e32 v142, v228
	s_nop 0
	s_nop 1
	v_mov_b32_e32 v134, v212
	v_mov_b32_e32 v135, v213
	v_mov_b32_e32 v136, v214
	v_mov_b32_e32 v137, v215
	s_nop 1
	v_mov_b32_e32 v138, v216
	v_mov_b32_e32 v139, v217
	v_mov_b32_e32 v140, v218
	v_mov_b32_e32 v141, v219
	v_fmamk_f32 v142, v142, 0x3a800000, v187
	v_rsq_f32_e32 v142, v142
	s_nop 0
	v_pk_mul_f32 v[172:173], v[110:111], v[142:143] op_sel_hi:[1,0]
	v_pk_mul_f32 v[190:191], v[112:113], v[142:143] op_sel_hi:[1,0]
	v_pk_mul_f32 v[192:193], v[102:103], v[142:143] op_sel_hi:[1,0]
	v_pk_mul_f32 v[194:195], v[104:105], v[142:143] op_sel_hi:[1,0]
	v_pk_mul_f32 v[190:191], v[190:191], v[190:191]
	v_pk_mul_f32 v[172:173], v[172:173], v[172:173]
	v_pk_mul_f32 v[194:195], v[194:195], v[194:195]
	v_pk_mul_f32 v[192:193], v[192:193], v[192:193]
	v_pk_mul_f32 v[196:197], v[108:109], v[142:143] op_sel_hi:[1,0]
	v_pk_mul_f32 v[200:201], v[106:107], v[142:143] op_sel_hi:[1,0]
	v_pk_mov_b32 v[210:211], v[172:173], v[190:191] op_sel:[1,0]
	v_mov_b32_e32 v173, v191
	v_pk_mov_b32 v[190:191], v[192:193], v[194:195] op_sel:[1,0]
	v_mov_b32_e32 v193, v195
	v_mul_f32_e32 v206, v200, v200
	v_mul_f32_e32 v208, v196, v196
	v_pk_add_f32 v[172:173], v[210:211], v[172:173]
	v_pk_add_f32 v[190:191], v[190:191], v[192:193]
	v_pk_mul_f32 v[202:203], v[100:101], v[142:143] op_sel_hi:[1,0]
	v_pk_mul_f32 v[204:205], v[98:99], v[142:143] op_sel_hi:[1,0]
	v_pk_fma_f32 v[194:195], v[200:201], v[200:201], v[206:207] op_sel_hi:[1,1,0]
	v_pk_fma_f32 v[196:197], v[196:197], v[196:197], v[208:209] op_sel_hi:[1,1,0]
	v_pk_add_f32 v[172:173], v[172:173], v[172:173] op_sel_hi:[0,1]
	v_pk_add_f32 v[190:191], v[190:191], v[190:191] op_sel_hi:[0,1]
	v_mul_f32_e32 v194, v204, v204
	v_mul_f32_e32 v196, v205, v205
	v_mul_f32_e32 v172, v202, v202
	v_mul_f32_e32 v190, v203, v203
	v_pk_add_f32 v[192:193], v[194:195], v[196:197]
	v_pk_add_f32 v[172:173], v[172:173], v[190:191]
	s_nop 0
	v_pk_add_f32 v[172:173], v[192:193], v[172:173]
	s_nop 0
	v_add_f32_e32 v143, v172, v173
	ds_bpermute_b32 v167, v132, v143
	s_waitcnt lgkmcnt(0)
	v_add_f32_e32 v143, v143, v167
	ds_bpermute_b32 v167, v133, v143
	s_waitcnt lgkmcnt(0)
	v_add_f32_e32 v143, v143, v167
	v_fmamk_f32 v143, v143, 0x3c800000, v187
	v_rsq_f32_e32 v143, v143
	s_nop 0
	v_mul_f32_e32 v142, v142, v143
	v_mul_f32_e32 v142, 0x3e38aa3b, v142
	v_pk_mul_f32 v[172:173], v[110:111], v[142:143] op_sel_hi:[1,0]
	v_pk_mul_f32 v[190:191], v[112:113], v[142:143] op_sel_hi:[1,0]
	v_pk_mul_f32 v[192:193], v[102:103], v[142:143] op_sel_hi:[1,0]
	v_pk_mul_f32 v[194:195], v[104:105], v[142:143] op_sel_hi:[1,0]
	v_pk_mul_f32 v[136:137], v[136:137], v[190:191]
	v_pk_mul_f32 v[134:135], v[134:135], v[172:173]
	v_pk_mul_f32 v[140:141], v[140:141], v[194:195]
	v_pk_mul_f32 v[138:139], v[138:139], v[192:193]
	v_cvt_pk_bf16_f32 v134, v134, v135
	v_cvt_pk_bf16_f32 v135, v136, v137
	v_cvt_pk_bf16_f32 v136, v138, v139
	v_cvt_pk_bf16_f32 v137, v140, v141
	global_store_dwordx4 v[144:145], v[134:137], off
	s_nop 1
	v_mov_b32_e32 v134, v220
	v_mov_b32_e32 v135, v221
	v_mov_b32_e32 v136, v222
	v_mov_b32_e32 v137, v223
	s_nop 0
	s_nop 1
	v_mov_b32_e32 v138, v224
	v_mov_b32_e32 v139, v225
	v_mov_b32_e32 v140, v226
	v_mov_b32_e32 v141, v227
	v_pk_mul_f32 v[192:193], v[106:107], v[142:143] op_sel_hi:[1,0]
	v_pk_mul_f32 v[194:195], v[108:109], v[142:143] op_sel_hi:[1,0]
	v_pk_mul_f32 v[196:197], v[98:99], v[142:143] op_sel_hi:[1,0]
	v_pk_mul_f32 v[142:143], v[100:101], v[142:143] op_sel_hi:[1,0]
	v_or_b32_e32 v172, 32, v166
	v_ashrrev_i32_e32 v173, 31, v172
	v_lshl_add_u64 v[190:191], v[172:173], 2, s[16:17]
	v_pk_mul_f32 v[136:137], v[136:137], v[194:195]
	v_pk_mul_f32 v[134:135], v[134:135], v[192:193]
	v_pk_mul_f32 v[140:141], v[140:141], v[142:143]
	v_pk_mul_f32 v[138:139], v[138:139], v[196:197]
	v_cvt_pk_bf16_f32 v134, v134, v135
	v_cvt_pk_bf16_f32 v135, v136, v137
	v_cvt_pk_bf16_f32 v136, v138, v139
	v_cvt_pk_bf16_f32 v137, v140, v141
	global_store_dwordx4 v[144:145], v[134:137], off offset:64
	s_nop 1
	v_mov_b32_e32 v142, v229
	s_nop 0
	s_nop 1
	v_mov_b32_e32 v134, v212
	v_mov_b32_e32 v135, v213
	v_mov_b32_e32 v136, v214
	v_mov_b32_e32 v137, v215
	s_nop 1
	v_mov_b32_e32 v138, v216
	v_mov_b32_e32 v139, v217
	v_mov_b32_e32 v140, v218
	v_mov_b32_e32 v141, v219
	v_fmamk_f32 v142, v142, 0x3a800000, v187
	v_rsq_f32_e32 v142, v142
	s_nop 0
	v_pk_mul_f32 v[144:145], v[94:95], v[142:143] op_sel_hi:[1,0]
	v_pk_mul_f32 v[190:191], v[96:97], v[142:143] op_sel_hi:[1,0]
	v_pk_mul_f32 v[192:193], v[86:87], v[142:143] op_sel_hi:[1,0]
	v_pk_mul_f32 v[194:195], v[88:89], v[142:143] op_sel_hi:[1,0]
	v_pk_mul_f32 v[190:191], v[190:191], v[190:191]
	v_pk_mul_f32 v[144:145], v[144:145], v[144:145]
	v_pk_mul_f32 v[194:195], v[194:195], v[194:195]
	v_pk_mul_f32 v[192:193], v[192:193], v[192:193]
	v_pk_mul_f32 v[196:197], v[92:93], v[142:143] op_sel_hi:[1,0]
	v_pk_mul_f32 v[200:201], v[90:91], v[142:143] op_sel_hi:[1,0]
	v_pk_mov_b32 v[210:211], v[144:145], v[190:191] op_sel:[1,0]
	v_mov_b32_e32 v145, v191
	v_pk_mov_b32 v[190:191], v[192:193], v[194:195] op_sel:[1,0]
	v_mov_b32_e32 v193, v195
	v_mul_f32_e32 v206, v200, v200
	v_mul_f32_e32 v208, v196, v196
	v_pk_add_f32 v[144:145], v[210:211], v[144:145]
	v_pk_add_f32 v[190:191], v[190:191], v[192:193]
	v_pk_mul_f32 v[202:203], v[84:85], v[142:143] op_sel_hi:[1,0]
	v_pk_mul_f32 v[204:205], v[82:83], v[142:143] op_sel_hi:[1,0]
	v_pk_fma_f32 v[194:195], v[200:201], v[200:201], v[206:207] op_sel_hi:[1,1,0]
	v_pk_fma_f32 v[196:197], v[196:197], v[196:197], v[208:209] op_sel_hi:[1,1,0]
	v_pk_add_f32 v[144:145], v[144:145], v[144:145] op_sel_hi:[0,1]
	v_pk_add_f32 v[190:191], v[190:191], v[190:191] op_sel_hi:[0,1]
	v_mul_f32_e32 v194, v204, v204
	v_mul_f32_e32 v196, v205, v205
	v_mul_f32_e32 v144, v202, v202
	v_mul_f32_e32 v190, v203, v203
	v_pk_add_f32 v[192:193], v[194:195], v[196:197]
	v_pk_add_f32 v[144:145], v[144:145], v[190:191]
	s_nop 0
	v_pk_add_f32 v[144:145], v[192:193], v[144:145]
	s_nop 0
	v_add_f32_e32 v143, v144, v145
	ds_bpermute_b32 v144, v132, v143
	s_waitcnt lgkmcnt(0)
	v_add_f32_e32 v143, v143, v144
	ds_bpermute_b32 v144, v133, v143
	s_waitcnt lgkmcnt(0)
	v_add_f32_e32 v143, v143, v144
	v_fmamk_f32 v143, v143, 0x3c800000, v187
	v_rsq_f32_e32 v143, v143
	v_lshlrev_b64 v[144:145], 9, v[172:173]
	v_lshl_add_u64 v[144:145], v[156:157], 0, v[144:145]
	v_mul_f32_e32 v142, v142, v143
	v_mul_f32_e32 v142, 0x3e38aa3b, v142
	v_pk_mul_f32 v[172:173], v[94:95], v[142:143] op_sel_hi:[1,0]
	v_pk_mul_f32 v[190:191], v[96:97], v[142:143] op_sel_hi:[1,0]
	v_pk_mul_f32 v[192:193], v[86:87], v[142:143] op_sel_hi:[1,0]
	v_pk_mul_f32 v[194:195], v[88:89], v[142:143] op_sel_hi:[1,0]
	v_pk_mul_f32 v[136:137], v[136:137], v[190:191]
	v_pk_mul_f32 v[134:135], v[134:135], v[172:173]
	v_pk_mul_f32 v[140:141], v[140:141], v[194:195]
	v_pk_mul_f32 v[138:139], v[138:139], v[192:193]
	v_cvt_pk_bf16_f32 v134, v134, v135
	v_cvt_pk_bf16_f32 v135, v136, v137
	v_cvt_pk_bf16_f32 v136, v138, v139
	v_cvt_pk_bf16_f32 v137, v140, v141
	global_store_dwordx4 v[144:145], v[134:137], off
	s_nop 1
	v_mov_b32_e32 v134, v220
	v_mov_b32_e32 v135, v221
	v_mov_b32_e32 v136, v222
	v_mov_b32_e32 v137, v223
	s_nop 0
	s_nop 1
	v_mov_b32_e32 v138, v224
	v_mov_b32_e32 v139, v225
	v_mov_b32_e32 v140, v226
	v_mov_b32_e32 v141, v227
	v_pk_mul_f32 v[192:193], v[90:91], v[142:143] op_sel_hi:[1,0]
	v_pk_mul_f32 v[194:195], v[92:93], v[142:143] op_sel_hi:[1,0]
	v_pk_mul_f32 v[196:197], v[82:83], v[142:143] op_sel_hi:[1,0]
	v_pk_mul_f32 v[142:143], v[84:85], v[142:143] op_sel_hi:[1,0]
	v_or_b32_e32 v172, 48, v166
	v_ashrrev_i32_e32 v173, 31, v172
	v_lshl_add_u64 v[190:191], v[172:173], 2, s[16:17]
	v_pk_mul_f32 v[136:137], v[136:137], v[194:195]
	v_pk_mul_f32 v[134:135], v[134:135], v[192:193]
	v_pk_mul_f32 v[140:141], v[140:141], v[142:143]
	v_pk_mul_f32 v[138:139], v[138:139], v[196:197]
	v_cvt_pk_bf16_f32 v134, v134, v135
	v_cvt_pk_bf16_f32 v135, v136, v137
	v_cvt_pk_bf16_f32 v136, v138, v139
	v_cvt_pk_bf16_f32 v137, v140, v141
	global_store_dwordx4 v[144:145], v[134:137], off offset:64
	s_nop 1
	v_mov_b32_e32 v142, v230
	s_nop 0
	s_nop 1
	v_mov_b32_e32 v134, v212
	v_mov_b32_e32 v135, v213
	v_mov_b32_e32 v136, v214
	v_mov_b32_e32 v137, v215
	s_nop 1
	v_mov_b32_e32 v138, v216
	v_mov_b32_e32 v139, v217
	v_mov_b32_e32 v140, v218
	v_mov_b32_e32 v141, v219
	v_fmamk_f32 v142, v142, 0x3a800000, v187
	v_rsq_f32_e32 v142, v142
	s_nop 0
	v_pk_mul_f32 v[144:145], v[78:79], v[142:143] op_sel_hi:[1,0]
	v_pk_mul_f32 v[190:191], v[80:81], v[142:143] op_sel_hi:[1,0]
	v_pk_mul_f32 v[192:193], v[70:71], v[142:143] op_sel_hi:[1,0]
	v_pk_mul_f32 v[194:195], v[72:73], v[142:143] op_sel_hi:[1,0]
	v_pk_mul_f32 v[190:191], v[190:191], v[190:191]
	v_pk_mul_f32 v[144:145], v[144:145], v[144:145]
	v_pk_mul_f32 v[194:195], v[194:195], v[194:195]
	v_pk_mul_f32 v[192:193], v[192:193], v[192:193]
	v_pk_mul_f32 v[196:197], v[76:77], v[142:143] op_sel_hi:[1,0]
	v_pk_mul_f32 v[200:201], v[74:75], v[142:143] op_sel_hi:[1,0]
	v_pk_mov_b32 v[210:211], v[144:145], v[190:191] op_sel:[1,0]
	v_mov_b32_e32 v145, v191
	v_pk_mov_b32 v[190:191], v[192:193], v[194:195] op_sel:[1,0]
	v_mov_b32_e32 v193, v195
	v_mul_f32_e32 v206, v200, v200
	v_mul_f32_e32 v208, v196, v196
	v_pk_add_f32 v[144:145], v[210:211], v[144:145]
	v_pk_add_f32 v[190:191], v[190:191], v[192:193]
	v_pk_mul_f32 v[202:203], v[68:69], v[142:143] op_sel_hi:[1,0]
	v_pk_mul_f32 v[204:205], v[66:67], v[142:143] op_sel_hi:[1,0]
	v_pk_fma_f32 v[194:195], v[200:201], v[200:201], v[206:207] op_sel_hi:[1,1,0]
	v_pk_fma_f32 v[196:197], v[196:197], v[196:197], v[208:209] op_sel_hi:[1,1,0]
	v_pk_add_f32 v[144:145], v[144:145], v[144:145] op_sel_hi:[0,1]
	v_pk_add_f32 v[190:191], v[190:191], v[190:191] op_sel_hi:[0,1]
	v_mul_f32_e32 v194, v204, v204
	v_mul_f32_e32 v196, v205, v205
	v_mul_f32_e32 v144, v202, v202
	v_mul_f32_e32 v190, v203, v203
	v_pk_add_f32 v[192:193], v[194:195], v[196:197]
	v_pk_add_f32 v[144:145], v[144:145], v[190:191]
	s_nop 0
	v_pk_add_f32 v[144:145], v[192:193], v[144:145]
	s_nop 0
	v_add_f32_e32 v143, v144, v145
	ds_bpermute_b32 v144, v132, v143
	s_waitcnt lgkmcnt(0)
	v_add_f32_e32 v143, v143, v144
	ds_bpermute_b32 v144, v133, v143
	s_waitcnt lgkmcnt(0)
	v_add_f32_e32 v143, v143, v144
	v_fmamk_f32 v143, v143, 0x3c800000, v187
	v_rsq_f32_e32 v143, v143
	v_lshlrev_b64 v[144:145], 9, v[172:173]
	v_lshl_add_u64 v[144:145], v[156:157], 0, v[144:145]
	v_mul_f32_e32 v142, v142, v143
	v_mul_f32_e32 v142, 0x3e38aa3b, v142
	v_pk_mul_f32 v[172:173], v[78:79], v[142:143] op_sel_hi:[1,0]
	v_pk_mul_f32 v[190:191], v[80:81], v[142:143] op_sel_hi:[1,0]
	v_pk_mul_f32 v[192:193], v[70:71], v[142:143] op_sel_hi:[1,0]
	v_pk_mul_f32 v[194:195], v[72:73], v[142:143] op_sel_hi:[1,0]
	v_pk_mul_f32 v[136:137], v[136:137], v[190:191]
	v_pk_mul_f32 v[134:135], v[134:135], v[172:173]
	v_pk_mul_f32 v[140:141], v[140:141], v[194:195]
	v_pk_mul_f32 v[138:139], v[138:139], v[192:193]
	v_cvt_pk_bf16_f32 v134, v134, v135
	v_cvt_pk_bf16_f32 v135, v136, v137
	v_cvt_pk_bf16_f32 v136, v138, v139
	v_cvt_pk_bf16_f32 v137, v140, v141
	global_store_dwordx4 v[144:145], v[134:137], off
	s_nop 1
	v_mov_b32_e32 v134, v220
	v_mov_b32_e32 v135, v221
	v_mov_b32_e32 v136, v222
	v_mov_b32_e32 v137, v223
	s_nop 0
	s_nop 1
	v_mov_b32_e32 v138, v224
	v_mov_b32_e32 v139, v225
	v_mov_b32_e32 v140, v226
	v_mov_b32_e32 v141, v227
	v_pk_mul_f32 v[172:173], v[74:75], v[142:143] op_sel_hi:[1,0]
	v_pk_mul_f32 v[190:191], v[76:77], v[142:143] op_sel_hi:[1,0]
	v_pk_mul_f32 v[192:193], v[66:67], v[142:143] op_sel_hi:[1,0]
	v_pk_mul_f32 v[142:143], v[68:69], v[142:143] op_sel_hi:[1,0]
	v_pk_mul_f32 v[136:137], v[136:137], v[190:191]
	v_pk_mul_f32 v[134:135], v[134:135], v[172:173]
	v_pk_mul_f32 v[140:141], v[140:141], v[142:143]
	v_pk_mul_f32 v[138:139], v[138:139], v[192:193]
	v_cvt_pk_bf16_f32 v134, v134, v135
	v_cvt_pk_bf16_f32 v135, v136, v137
	v_cvt_pk_bf16_f32 v136, v138, v139
	v_cvt_pk_bf16_f32 v137, v140, v141
	global_store_dwordx4 v[144:145], v[134:137], off offset:64
	s_nop 1
	v_mov_b32_e32 v142, v231
	s_nop 0
	s_nop 1
	v_mov_b32_e32 v134, v212
	v_mov_b32_e32 v135, v213
	v_mov_b32_e32 v136, v214
	v_mov_b32_e32 v137, v215
	s_nop 1
	v_mov_b32_e32 v138, v216
	v_mov_b32_e32 v139, v217
	v_mov_b32_e32 v140, v218
	v_mov_b32_e32 v141, v219
	v_fmamk_f32 v142, v142, 0x3a800000, v187
	v_rsq_f32_e32 v142, v142
	s_nop 0
	v_pk_mul_f32 v[144:145], v[62:63], v[142:143] op_sel_hi:[1,0]
	v_pk_mul_f32 v[172:173], v[64:65], v[142:143] op_sel_hi:[1,0]
	v_pk_mul_f32 v[190:191], v[54:55], v[142:143] op_sel_hi:[1,0]
	v_pk_mul_f32 v[192:193], v[56:57], v[142:143] op_sel_hi:[1,0]
	v_pk_mul_f32 v[172:173], v[172:173], v[172:173]
	v_pk_mul_f32 v[144:145], v[144:145], v[144:145]
	v_pk_mul_f32 v[192:193], v[192:193], v[192:193]
	v_pk_mul_f32 v[190:191], v[190:191], v[190:191]
	v_pk_mul_f32 v[194:195], v[60:61], v[142:143] op_sel_hi:[1,0]
	v_pk_mul_f32 v[196:197], v[58:59], v[142:143] op_sel_hi:[1,0]
	v_pk_mov_b32 v[208:209], v[144:145], v[172:173] op_sel:[1,0]
	v_mov_b32_e32 v145, v173
	v_pk_mov_b32 v[172:173], v[190:191], v[192:193] op_sel:[1,0]
	v_mov_b32_e32 v191, v193
	v_mul_f32_e32 v204, v196, v196
	v_mul_f32_e32 v206, v194, v194
	v_pk_add_f32 v[144:145], v[208:209], v[144:145]
	v_pk_add_f32 v[172:173], v[172:173], v[190:191]
	v_pk_mul_f32 v[200:201], v[52:53], v[142:143] op_sel_hi:[1,0]
	v_pk_mul_f32 v[202:203], v[50:51], v[142:143] op_sel_hi:[1,0]
	v_pk_fma_f32 v[192:193], v[196:197], v[196:197], v[204:205] op_sel_hi:[1,1,0]
	v_pk_fma_f32 v[194:195], v[194:195], v[194:195], v[206:207] op_sel_hi:[1,1,0]
	v_pk_add_f32 v[144:145], v[144:145], v[144:145] op_sel_hi:[0,1]
	v_pk_add_f32 v[172:173], v[172:173], v[172:173] op_sel_hi:[0,1]
	v_mul_f32_e32 v192, v202, v202
	v_mul_f32_e32 v194, v203, v203
	v_mul_f32_e32 v144, v200, v200
	v_mul_f32_e32 v172, v201, v201
	v_pk_add_f32 v[190:191], v[192:193], v[194:195]
	v_pk_add_f32 v[144:145], v[144:145], v[172:173]
	s_nop 0
	v_pk_add_f32 v[144:145], v[190:191], v[144:145]
	s_nop 0
	v_add_f32_e32 v143, v144, v145
	ds_bpermute_b32 v144, v132, v143
	s_waitcnt lgkmcnt(0)
	v_add_f32_e32 v143, v143, v144
	ds_bpermute_b32 v144, v133, v143
	s_waitcnt lgkmcnt(0)
	v_add_f32_e32 v143, v143, v144
	v_fmamk_f32 v143, v143, 0x3c800000, v187
	v_rsq_f32_e32 v143, v143
	v_add_co_u32_e32 v144, vcc, s0, v130
	s_mov_b32 s0, 0x12000
	v_mul_f32_e32 v142, v142, v143
	v_mul_f32_e32 v142, 0x3e38aa3b, v142
	v_pk_mul_f32 v[172:173], v[62:63], v[142:143] op_sel_hi:[1,0]
	v_pk_mul_f32 v[190:191], v[64:65], v[142:143] op_sel_hi:[1,0]
	v_pk_mul_f32 v[192:193], v[54:55], v[142:143] op_sel_hi:[1,0]
	v_pk_mul_f32 v[194:195], v[56:57], v[142:143] op_sel_hi:[1,0]
	v_pk_mul_f32 v[136:137], v[136:137], v[190:191]
	v_pk_mul_f32 v[134:135], v[134:135], v[172:173]
	v_pk_mul_f32 v[140:141], v[140:141], v[194:195]
	v_pk_mul_f32 v[138:139], v[138:139], v[192:193]
	v_addc_co_u32_e32 v145, vcc, 0, v131, vcc
	v_cvt_pk_bf16_f32 v134, v134, v135
	v_cvt_pk_bf16_f32 v135, v136, v137
	v_cvt_pk_bf16_f32 v136, v138, v139
	v_cvt_pk_bf16_f32 v137, v140, v141
	global_store_dwordx4 v[144:145], v[134:137], off
	s_nop 1
	v_mov_b32_e32 v134, v220
	v_mov_b32_e32 v135, v221
	v_mov_b32_e32 v136, v222
	v_mov_b32_e32 v137, v223
	s_nop 0
	s_nop 1
	v_mov_b32_e32 v138, v224
	v_mov_b32_e32 v139, v225
	v_mov_b32_e32 v140, v226
	v_mov_b32_e32 v141, v227
	v_pk_mul_f32 v[172:173], v[58:59], v[142:143] op_sel_hi:[1,0]
	v_pk_mul_f32 v[190:191], v[60:61], v[142:143] op_sel_hi:[1,0]
	v_pk_mul_f32 v[192:193], v[50:51], v[142:143] op_sel_hi:[1,0]
	v_pk_mul_f32 v[142:143], v[52:53], v[142:143] op_sel_hi:[1,0]
	v_lshl_add_u64 v[144:145], v[130:131], 0, s[22:23]
	v_pk_mul_f32 v[136:137], v[136:137], v[190:191]
	v_pk_mul_f32 v[134:135], v[134:135], v[172:173]
	v_pk_mul_f32 v[140:141], v[140:141], v[142:143]
	v_pk_mul_f32 v[138:139], v[138:139], v[192:193]
	v_cvt_pk_bf16_f32 v134, v134, v135
	v_cvt_pk_bf16_f32 v135, v136, v137
	v_cvt_pk_bf16_f32 v136, v138, v139
	v_cvt_pk_bf16_f32 v137, v140, v141
	global_store_dwordx4 v[144:145], v[134:137], off offset:64
	s_nop 1
	v_mov_b32_e32 v142, v232
	s_nop 0
	s_nop 1
	v_mov_b32_e32 v134, v212
	v_mov_b32_e32 v135, v213
	v_mov_b32_e32 v136, v214
	v_mov_b32_e32 v137, v215
	s_nop 1
	v_mov_b32_e32 v138, v216
	v_mov_b32_e32 v139, v217
	v_mov_b32_e32 v140, v218
	v_mov_b32_e32 v141, v219
	v_fmamk_f32 v142, v142, 0x3a800000, v187
	v_rsq_f32_e32 v142, v142
	s_nop 0
	v_pk_mul_f32 v[144:145], v[46:47], v[142:143] op_sel_hi:[1,0]
	v_pk_mul_f32 v[172:173], v[48:49], v[142:143] op_sel_hi:[1,0]
	v_pk_mul_f32 v[190:191], v[38:39], v[142:143] op_sel_hi:[1,0]
	v_pk_mul_f32 v[192:193], v[40:41], v[142:143] op_sel_hi:[1,0]
	v_pk_mul_f32 v[172:173], v[172:173], v[172:173]
	v_pk_mul_f32 v[144:145], v[144:145], v[144:145]
	v_pk_mul_f32 v[192:193], v[192:193], v[192:193]
	v_pk_mul_f32 v[190:191], v[190:191], v[190:191]
	v_pk_mul_f32 v[194:195], v[44:45], v[142:143] op_sel_hi:[1,0]
	v_pk_mul_f32 v[196:197], v[42:43], v[142:143] op_sel_hi:[1,0]
	v_pk_mov_b32 v[208:209], v[144:145], v[172:173] op_sel:[1,0]
	v_mov_b32_e32 v145, v173
	v_pk_mov_b32 v[172:173], v[190:191], v[192:193] op_sel:[1,0]
	v_mov_b32_e32 v191, v193
	v_mul_f32_e32 v204, v196, v196
	v_mul_f32_e32 v206, v194, v194
	v_pk_add_f32 v[144:145], v[208:209], v[144:145]
	v_pk_add_f32 v[172:173], v[172:173], v[190:191]
	v_pk_mul_f32 v[200:201], v[36:37], v[142:143] op_sel_hi:[1,0]
	v_pk_mul_f32 v[202:203], v[34:35], v[142:143] op_sel_hi:[1,0]
	v_pk_fma_f32 v[192:193], v[196:197], v[196:197], v[204:205] op_sel_hi:[1,1,0]
	v_pk_fma_f32 v[194:195], v[194:195], v[194:195], v[206:207] op_sel_hi:[1,1,0]
	v_pk_add_f32 v[144:145], v[144:145], v[144:145] op_sel_hi:[0,1]
	v_pk_add_f32 v[172:173], v[172:173], v[172:173] op_sel_hi:[0,1]
	v_mul_f32_e32 v192, v202, v202
	v_mul_f32_e32 v194, v203, v203
	v_mul_f32_e32 v144, v200, v200
	v_mul_f32_e32 v172, v201, v201
	v_pk_add_f32 v[190:191], v[192:193], v[194:195]
	v_pk_add_f32 v[144:145], v[144:145], v[172:173]
	s_nop 0
	v_pk_add_f32 v[144:145], v[190:191], v[144:145]
	s_nop 0
	v_add_f32_e32 v143, v144, v145
	ds_bpermute_b32 v144, v132, v143
	s_waitcnt lgkmcnt(0)
	v_add_f32_e32 v143, v143, v144
	ds_bpermute_b32 v144, v133, v143
	s_waitcnt lgkmcnt(0)
	v_add_f32_e32 v143, v143, v144
	v_fmamk_f32 v143, v143, 0x3c800000, v187
	v_rsq_f32_e32 v143, v143
	v_add_co_u32_e32 v144, vcc, s0, v130
	s_mov_b32 s0, 0x14000
	v_mul_f32_e32 v142, v142, v143
	v_mul_f32_e32 v142, 0x3e38aa3b, v142
	v_pk_mul_f32 v[172:173], v[46:47], v[142:143] op_sel_hi:[1,0]
	v_pk_mul_f32 v[190:191], v[48:49], v[142:143] op_sel_hi:[1,0]
	v_pk_mul_f32 v[192:193], v[38:39], v[142:143] op_sel_hi:[1,0]
	v_pk_mul_f32 v[194:195], v[40:41], v[142:143] op_sel_hi:[1,0]
	v_pk_mul_f32 v[136:137], v[136:137], v[190:191]
	v_pk_mul_f32 v[134:135], v[134:135], v[172:173]
	v_pk_mul_f32 v[140:141], v[140:141], v[194:195]
	v_pk_mul_f32 v[138:139], v[138:139], v[192:193]
	v_addc_co_u32_e32 v145, vcc, 0, v131, vcc
	v_cvt_pk_bf16_f32 v134, v134, v135
	v_cvt_pk_bf16_f32 v135, v136, v137
	v_cvt_pk_bf16_f32 v136, v138, v139
	v_cvt_pk_bf16_f32 v137, v140, v141
	global_store_dwordx4 v[144:145], v[134:137], off
	s_nop 1
	v_mov_b32_e32 v134, v220
	v_mov_b32_e32 v135, v221
	v_mov_b32_e32 v136, v222
	v_mov_b32_e32 v137, v223
	s_nop 0
	s_nop 1
	v_mov_b32_e32 v138, v224
	v_mov_b32_e32 v139, v225
	v_mov_b32_e32 v140, v226
	v_mov_b32_e32 v141, v227
	v_pk_mul_f32 v[172:173], v[42:43], v[142:143] op_sel_hi:[1,0]
	v_pk_mul_f32 v[190:191], v[44:45], v[142:143] op_sel_hi:[1,0]
	v_pk_mul_f32 v[192:193], v[34:35], v[142:143] op_sel_hi:[1,0]
	v_pk_mul_f32 v[142:143], v[36:37], v[142:143] op_sel_hi:[1,0]
	v_lshl_add_u64 v[144:145], v[130:131], 0, s[24:25]
	v_pk_mul_f32 v[136:137], v[136:137], v[190:191]
	v_pk_mul_f32 v[134:135], v[134:135], v[172:173]
	v_pk_mul_f32 v[140:141], v[140:141], v[142:143]
	v_pk_mul_f32 v[138:139], v[138:139], v[192:193]
	v_cvt_pk_bf16_f32 v134, v134, v135
	v_cvt_pk_bf16_f32 v135, v136, v137
	v_cvt_pk_bf16_f32 v136, v138, v139
	v_cvt_pk_bf16_f32 v137, v140, v141
	global_store_dwordx4 v[144:145], v[134:137], off offset:64
	s_nop 1
	v_mov_b32_e32 v142, v233
	s_nop 0
	s_nop 1
	v_mov_b32_e32 v134, v212
	v_mov_b32_e32 v135, v213
	v_mov_b32_e32 v136, v214
	v_mov_b32_e32 v137, v215
	s_nop 1
	v_mov_b32_e32 v138, v216
	v_mov_b32_e32 v139, v217
	v_mov_b32_e32 v140, v218
	v_mov_b32_e32 v141, v219
	v_fmamk_f32 v142, v142, 0x3a800000, v187
	v_rsq_f32_e32 v142, v142
	s_nop 0
	v_pk_mul_f32 v[144:145], v[30:31], v[142:143] op_sel_hi:[1,0]
	v_pk_mul_f32 v[172:173], v[32:33], v[142:143] op_sel_hi:[1,0]
	v_pk_mul_f32 v[190:191], v[22:23], v[142:143] op_sel_hi:[1,0]
	v_pk_mul_f32 v[192:193], v[24:25], v[142:143] op_sel_hi:[1,0]
	v_pk_mul_f32 v[172:173], v[172:173], v[172:173]
	v_pk_mul_f32 v[144:145], v[144:145], v[144:145]
	v_pk_mul_f32 v[192:193], v[192:193], v[192:193]
	v_pk_mul_f32 v[190:191], v[190:191], v[190:191]
	v_pk_mul_f32 v[194:195], v[28:29], v[142:143] op_sel_hi:[1,0]
	v_pk_mul_f32 v[196:197], v[26:27], v[142:143] op_sel_hi:[1,0]
	v_pk_mov_b32 v[208:209], v[144:145], v[172:173] op_sel:[1,0]
	v_mov_b32_e32 v145, v173
	v_pk_mov_b32 v[172:173], v[190:191], v[192:193] op_sel:[1,0]
	v_mov_b32_e32 v191, v193
	v_mul_f32_e32 v204, v196, v196
	v_mul_f32_e32 v206, v194, v194
	v_pk_add_f32 v[144:145], v[208:209], v[144:145]
	v_pk_add_f32 v[172:173], v[172:173], v[190:191]
	v_pk_mul_f32 v[200:201], v[20:21], v[142:143] op_sel_hi:[1,0]
	v_pk_mul_f32 v[202:203], v[18:19], v[142:143] op_sel_hi:[1,0]
	v_pk_fma_f32 v[192:193], v[196:197], v[196:197], v[204:205] op_sel_hi:[1,1,0]
	v_pk_fma_f32 v[194:195], v[194:195], v[194:195], v[206:207] op_sel_hi:[1,1,0]
	v_pk_add_f32 v[144:145], v[144:145], v[144:145] op_sel_hi:[0,1]
	v_pk_add_f32 v[172:173], v[172:173], v[172:173] op_sel_hi:[0,1]
	v_mul_f32_e32 v192, v202, v202
	v_mul_f32_e32 v194, v203, v203
	v_mul_f32_e32 v144, v200, v200
	v_mul_f32_e32 v172, v201, v201
	v_pk_add_f32 v[190:191], v[192:193], v[194:195]
	v_pk_add_f32 v[144:145], v[144:145], v[172:173]
	s_nop 0
	v_pk_add_f32 v[144:145], v[190:191], v[144:145]
	s_nop 0
	v_add_f32_e32 v143, v144, v145
	ds_bpermute_b32 v144, v132, v143
	s_waitcnt lgkmcnt(0)
	v_add_f32_e32 v143, v143, v144
	ds_bpermute_b32 v144, v133, v143
	s_waitcnt lgkmcnt(0)
	v_add_f32_e32 v143, v143, v144
	v_fmamk_f32 v143, v143, 0x3c800000, v187
	v_rsq_f32_e32 v143, v143
	v_add_co_u32_e32 v144, vcc, s0, v130
	s_mov_b32 s0, 0x16000
	v_mul_f32_e32 v142, v142, v143
	v_mul_f32_e32 v142, 0x3e38aa3b, v142
	v_pk_mul_f32 v[172:173], v[30:31], v[142:143] op_sel_hi:[1,0]
	v_pk_mul_f32 v[190:191], v[32:33], v[142:143] op_sel_hi:[1,0]
	v_pk_mul_f32 v[192:193], v[22:23], v[142:143] op_sel_hi:[1,0]
	v_pk_mul_f32 v[194:195], v[24:25], v[142:143] op_sel_hi:[1,0]
	v_pk_mul_f32 v[136:137], v[136:137], v[190:191]
	v_pk_mul_f32 v[134:135], v[134:135], v[172:173]
	v_pk_mul_f32 v[140:141], v[140:141], v[194:195]
	v_pk_mul_f32 v[138:139], v[138:139], v[192:193]
	v_addc_co_u32_e32 v145, vcc, 0, v131, vcc
	v_cvt_pk_bf16_f32 v134, v134, v135
	v_cvt_pk_bf16_f32 v135, v136, v137
	v_cvt_pk_bf16_f32 v136, v138, v139
	v_cvt_pk_bf16_f32 v137, v140, v141
	global_store_dwordx4 v[144:145], v[134:137], off
	s_nop 1
	v_mov_b32_e32 v134, v220
	v_mov_b32_e32 v135, v221
	v_mov_b32_e32 v136, v222
	v_mov_b32_e32 v137, v223
	s_nop 0
	s_nop 1
	v_mov_b32_e32 v138, v224
	v_mov_b32_e32 v139, v225
	v_mov_b32_e32 v140, v226
	v_mov_b32_e32 v141, v227
	v_pk_mul_f32 v[172:173], v[26:27], v[142:143] op_sel_hi:[1,0]
	v_pk_mul_f32 v[190:191], v[28:29], v[142:143] op_sel_hi:[1,0]
	v_pk_mul_f32 v[192:193], v[18:19], v[142:143] op_sel_hi:[1,0]
	v_pk_mul_f32 v[142:143], v[20:21], v[142:143] op_sel_hi:[1,0]
	v_lshl_add_u64 v[144:145], v[130:131], 0, s[26:27]
	v_pk_mul_f32 v[136:137], v[136:137], v[190:191]
	v_pk_mul_f32 v[134:135], v[134:135], v[172:173]
	v_pk_mul_f32 v[140:141], v[140:141], v[142:143]
	v_pk_mul_f32 v[138:139], v[138:139], v[192:193]
	v_cvt_pk_bf16_f32 v134, v134, v135
	v_cvt_pk_bf16_f32 v135, v136, v137
	v_cvt_pk_bf16_f32 v136, v138, v139
	v_cvt_pk_bf16_f32 v137, v140, v141
	global_store_dwordx4 v[144:145], v[134:137], off offset:64
	s_nop 1
	v_mov_b32_e32 v142, v234
	s_nop 0
	s_nop 1
	v_mov_b32_e32 v134, v212
	v_mov_b32_e32 v135, v213
	v_mov_b32_e32 v136, v214
	v_mov_b32_e32 v137, v215
	s_nop 1
	v_mov_b32_e32 v138, v216
	v_mov_b32_e32 v139, v217
	v_mov_b32_e32 v140, v218
	v_mov_b32_e32 v141, v219
	v_fmamk_f32 v142, v142, 0x3a800000, v187
	v_rsq_f32_e32 v142, v142
	s_nop 0
	v_pk_mul_f32 v[144:145], v[14:15], v[142:143] op_sel_hi:[1,0]
	v_pk_mul_f32 v[172:173], v[16:17], v[142:143] op_sel_hi:[1,0]
	v_pk_mul_f32 v[190:191], v[6:7], v[142:143] op_sel_hi:[1,0]
	v_pk_mul_f32 v[192:193], v[8:9], v[142:143] op_sel_hi:[1,0]
	v_pk_mul_f32 v[172:173], v[172:173], v[172:173]
	v_pk_mul_f32 v[144:145], v[144:145], v[144:145]
	v_pk_mul_f32 v[192:193], v[192:193], v[192:193]
	v_pk_mul_f32 v[190:191], v[190:191], v[190:191]
	v_pk_mul_f32 v[194:195], v[12:13], v[142:143] op_sel_hi:[1,0]
	v_pk_mul_f32 v[196:197], v[10:11], v[142:143] op_sel_hi:[1,0]
	v_pk_mov_b32 v[208:209], v[144:145], v[172:173] op_sel:[1,0]
	v_mov_b32_e32 v145, v173
	v_pk_mov_b32 v[172:173], v[190:191], v[192:193] op_sel:[1,0]
	v_mov_b32_e32 v191, v193
	v_mul_f32_e32 v204, v196, v196
	v_mul_f32_e32 v206, v194, v194
	v_pk_add_f32 v[144:145], v[208:209], v[144:145]
	v_pk_add_f32 v[172:173], v[172:173], v[190:191]
	v_pk_mul_f32 v[200:201], v[4:5], v[142:143] op_sel_hi:[1,0]
	v_pk_mul_f32 v[202:203], v[2:3], v[142:143] op_sel_hi:[1,0]
	v_pk_fma_f32 v[192:193], v[196:197], v[196:197], v[204:205] op_sel_hi:[1,1,0]
	v_pk_fma_f32 v[194:195], v[194:195], v[194:195], v[206:207] op_sel_hi:[1,1,0]
	v_pk_add_f32 v[144:145], v[144:145], v[144:145] op_sel_hi:[0,1]
	v_pk_add_f32 v[172:173], v[172:173], v[172:173] op_sel_hi:[0,1]
	v_mul_f32_e32 v192, v202, v202
	v_mul_f32_e32 v194, v203, v203
	v_mul_f32_e32 v144, v200, v200
	v_mul_f32_e32 v172, v201, v201
	v_pk_add_f32 v[190:191], v[192:193], v[194:195]
	v_pk_add_f32 v[144:145], v[144:145], v[172:173]
	s_nop 0
	v_pk_add_f32 v[144:145], v[190:191], v[144:145]
	s_nop 0
	v_add_f32_e32 v143, v144, v145
	ds_bpermute_b32 v132, v132, v143
	v_add_co_u32_e32 v144, vcc, s0, v130
	s_nop 1
	v_addc_co_u32_e32 v145, vcc, 0, v131, vcc
	s_waitcnt lgkmcnt(0)
	v_add_f32_e32 v132, v143, v132
	ds_bpermute_b32 v133, v133, v132
	s_waitcnt lgkmcnt(0)
	v_add_f32_e32 v132, v132, v133
	v_fmamk_f32 v132, v132, 0x3c800000, v187
	v_rsq_f32_e32 v132, v132
	s_nop 0
	v_mul_f32_e32 v132, v142, v132
	v_mul_f32_e32 v142, 0x3e38aa3b, v132
	v_pk_mul_f32 v[132:133], v[14:15], v[142:143] op_sel_hi:[1,0]
	v_pk_mul_f32 v[172:173], v[16:17], v[142:143] op_sel_hi:[1,0]
	v_pk_mul_f32 v[190:191], v[6:7], v[142:143] op_sel_hi:[1,0]
	v_pk_mul_f32 v[192:193], v[8:9], v[142:143] op_sel_hi:[1,0]
	v_pk_mul_f32 v[136:137], v[136:137], v[172:173]
	v_pk_mul_f32 v[132:133], v[134:135], v[132:133]
	v_pk_mul_f32 v[140:141], v[140:141], v[192:193]
	v_pk_mul_f32 v[134:135], v[138:139], v[190:191]
	v_cvt_pk_bf16_f32 v132, v132, v133
	v_cvt_pk_bf16_f32 v133, v136, v137
	v_cvt_pk_bf16_f32 v134, v134, v135
	v_cvt_pk_bf16_f32 v135, v140, v141
	global_store_dwordx4 v[144:145], v[132:135], off
	s_nop 1
	v_mov_b32_e32 v132, v220
	v_mov_b32_e32 v133, v221
	v_mov_b32_e32 v134, v222
	v_mov_b32_e32 v135, v223
	s_nop 0
	s_nop 1
	v_mov_b32_e32 v136, v224
	v_mov_b32_e32 v137, v225
	v_mov_b32_e32 v138, v226
	v_mov_b32_e32 v139, v227
	v_lshl_add_u64 v[140:141], v[130:131], 0, s[34:35]
	v_pk_mul_f32 v[130:131], v[10:11], v[142:143] op_sel_hi:[1,0]
	v_pk_mul_f32 v[144:145], v[12:13], v[142:143] op_sel_hi:[1,0]
	v_pk_mul_f32 v[172:173], v[2:3], v[142:143] op_sel_hi:[1,0]
	v_pk_mul_f32 v[142:143], v[4:5], v[142:143] op_sel_hi:[1,0]
	v_pk_mul_f32 v[134:135], v[134:135], v[144:145]
	v_pk_mul_f32 v[130:131], v[132:133], v[130:131]
	v_pk_mul_f32 v[138:139], v[138:139], v[142:143]
	v_pk_mul_f32 v[132:133], v[136:137], v[172:173]
	v_cvt_pk_bf16_f32 v130, v130, v131
	v_cvt_pk_bf16_f32 v131, v134, v135
	v_cvt_pk_bf16_f32 v132, v132, v133
	v_cvt_pk_bf16_f32 v133, v138, v139
	global_store_dwordx4 v[140:141], v[130:133], off offset:64
	s_cbranch_execnz .LBB0_164
